# residual-add epilogues: the 16 residual-tile loads issued ahead of the K-loop DMA drain and its barriers (on combined+final version)
# baseline (speedup 1.0000x reference)
; __device__ __forceinline__ float bf_lo(unsigned w) { return __uint_as_float(w << 16); }
; __device__ __forceinline__ float bf_hi(unsigned w) { return __uint_as_float(w & 0xffff0000u); }
; #define PG8_WAIT_V(n) asm volatile("s_waitcnt vmcnt(" #n ")" ::: "memory")
; #define PG8_BAR __builtin_amdgcn_s_barrier()
; template <class Epi, bool ALIGN_EPI = true>
; __device__ __forceinline__ void gemm_phase(LAS unsigned char* lds, const Gemm g, const Sched& S, const Epi& E) {
;     ...
;     PG8_WAIT_V(0);
;     if constexpr (!ALIGN_EPI) { if (wr == 0) PG8_BAR; }
;     PG8_BAR;
;     __device__ __forceinline__ void fused(f32x4 (&acc)[2][2][4][2], const Unit& u, int wr, int wc, int fr, int fq, LAS unsigned char* lds, int wid, int lane) const {
;     ...
;         const unsigned lo2 = (unsigned)(fr * DM + u.pn * BM + wc * 32 + 8 * fq) * 2u;
;         u32x4 hv[2][4][2];
; #pragma unroll
;         for (int ai = 0; ai < 2; ++ai)
; #pragma unroll
;             for (int m = 0; m < 4; ++m) { const char* hb2 = ROWG(HB, u, ai, m, wr, DM, 2);
; #pragma unroll
;                 for (int bj = 0; bj < 2; ++bj) hv[ai][m][bj] = *(const u32x4*)(hb2 + lo2 + bj * HALF * 2); }
; #pragma unroll
;         for (int ai = 0; ai < 2; ++ai)
; #pragma unroll
;             for (int m = 0; m < 4; ++m) { const int rl = ai * HALF + wr * 64 + m * 16 + fr; char* hb2 = ROWG(HB, u, ai, m, wr, DM, 2); float s = 0.f;
; #pragma unroll
;                 for (int bj = 0; bj < 2; ++bj) { const u32x4 w = hv[ai][m][bj];
;                     const f32x4 h0 = (f32x4){bf_lo(w.x), bf_hi(w.x), bf_lo(w.y), bf_hi(w.y)} + acc[ai][bj][m][0], h1 = (f32x4){bf_lo(w.z), bf_hi(w.z), bf_lo(w.w), bf_hi(w.w)} + acc[ai][bj][m][1];
;                     st_bf16x8((bf16_t*)(hb2 + lo2 + bj * HALF * 2), h0, h1);
;                     s += (h0[0] * h0[0] + h0[1] * h0[1]) + (h0[2] * h0[2] + h0[3] * h0[3]) + (h1[0] * h1[0] + h1[1] * h1[1]) + (h1[2] * h1[2] + h1[3] * h1[3]); }
;                 s += __shfl_xor(s, 16); s += __shfl_xor(s, 32);
;                 if (fq == 0) P[rl * 4 + wc] = s; }
.LBB0_1314:
	v_readlane_b32 s54, v246, 44
	v_readlane_b32 s55, v246, 45
	s_add_u32 s14, s54, s6
	v_and_b32_e32 v206, 63, v146
	s_addc_u32 s15, s55, s7
	s_lshl_b32 s6, s4, 9
	v_and_b32_e32 v207, 15, v206
	s_lshl_b32 s7, s5, 6
	v_and_b32_e32 v2, -16, v206
	v_lshlrev_b32_e32 v4, 12, v207
	s_or_b32 s6, s6, s7
	v_add3_u32 v2, s6, v2, v4
	s_lshl_b32 s6, s61, 8
	s_add_i32 s16, s6, s31
	s_ashr_i32 s17, s16, 31
	v_lshl_add_u64 v[4:5], s[14:15], 0, v[2:3]
	s_lshl_b64 s[42:43], s[16:17], 12
	v_lshl_add_u64 v[134:135], v[4:5], 0, s[42:43]
	global_load_dwordx4 v[194:197], v[134:135], off
	global_load_dwordx4 v[190:193], v[134:135], off offset:256
	s_or_b32 s18, s16, 16
	s_ashr_i32 s19, s18, 31
	s_lshl_b64 s[40:41], s[18:19], 12
	s_or_b32 s18, s16, 32
	s_ashr_i32 s19, s18, 31
	s_lshl_b64 s[26:27], s[18:19], 12
	s_or_b32 s18, s16, 48
	s_ashr_i32 s19, s18, 31
	s_lshl_b64 s[24:25], s[18:19], 12
	s_add_i32 s18, s16, 0x80
	s_ashr_i32 s19, s18, 31
	v_lshl_add_u64 v[134:135], v[4:5], 0, s[40:41]
	s_lshl_b64 s[22:23], s[18:19], 12
	s_add_i32 s18, s16, 0x90
	global_load_dwordx4 v[186:189], v[134:135], off
	global_load_dwordx4 v[182:185], v[134:135], off offset:256
	v_lshl_add_u64 v[134:135], v[4:5], 0, s[26:27]
	s_ashr_i32 s19, s18, 31
	global_load_dwordx4 v[178:181], v[134:135], off
	global_load_dwordx4 v[174:177], v[134:135], off offset:256
	v_lshl_add_u64 v[134:135], v[4:5], 0, s[24:25]
	s_lshl_b64 s[20:21], s[18:19], 12
	s_add_i32 s18, s16, 0xa0
	s_addk_i32 s16, 0xb0
	global_load_dwordx4 v[170:173], v[134:135], off
	global_load_dwordx4 v[166:169], v[134:135], off offset:256
	v_lshl_add_u64 v[134:135], v[4:5], 0, s[22:23]
	s_ashr_i32 s19, s18, 31
	s_ashr_i32 s17, s16, 31
	global_load_dwordx4 v[162:165], v[134:135], off
	global_load_dwordx4 v[158:161], v[134:135], off offset:256
	v_lshl_add_u64 v[134:135], v[4:5], 0, s[20:21]
	s_lshl_b64 s[18:19], s[18:19], 12
	s_lshl_b64 s[16:17], s[16:17], 12
	global_load_dwordx4 v[154:157], v[134:135], off
	global_load_dwordx4 v[150:153], v[134:135], off offset:256
	v_lshl_add_u64 v[134:135], v[4:5], 0, s[18:19]
	v_lshl_add_u64 v[4:5], v[4:5], 0, s[16:17]
	global_load_dwordx4 v[142:145], v[134:135], off
	s_nop 0
	global_load_dwordx4 v[134:137], v[134:135], off offset:256
	s_nop 0
	global_load_dwordx4 v[146:149], v[4:5], off
	global_load_dwordx4 v[138:141], v[4:5], off offset:256
	s_waitcnt vmcnt(0)
	s_cmpk_gt_u32 s30, 0xff
	s_cbranch_scc1 .LBB0_1316
	s_barrier
.LBB0_1316:
	v_readlane_b32 s52, v246, 42
	s_barrier
	v_and_b32_e32 v5, 64, v220
	v_xor_b32_e32 v4, 16, v220
	v_add_u32_e32 v5, 64, v5
	v_cmp_lt_i32_e32 vcc, v4, v5
	v_xor_b32_e32 v208, 32, v220
	s_lshl_b32 s5, s5, 2
	v_cndmask_b32_e32 v4, v220, v4, vcc
	v_cmp_lt_i32_e32 vcc, v208, v5
	s_add_i32 s5, s5, 0
	s_add_u32 s42, s14, s42
	v_cndmask_b32_e32 v5, v220, v208, vcc
	s_addc_u32 s43, s15, s43
	v_lshlrev_b32_e32 v4, 2, v4
	v_lshlrev_b32_e32 v5, 2, v5
	v_or_b32_e32 v207, s31, v207
	v_readlane_b32 s53, v246, 43
	v_cmp_gt_u32_e32 vcc, 16, v206
	s_waitcnt vmcnt(0)
	v_lshlrev_b32_e32 v208, 16, v194
	v_and_b32_e32 v209, 0xffff0000, v194
	v_lshlrev_b32_e32 v194, 16, v195
	v_and_b32_e32 v195, 0xffff0000, v195
	v_pk_add_f32 v[132:133], v[132:133], v[194:195]
	v_lshlrev_b32_e32 v194, 16, v196
	v_and_b32_e32 v195, 0xffff0000, v196
	v_lshlrev_b32_e32 v196, 16, v197
	v_and_b32_e32 v197, 0xffff0000, v197
	v_pk_add_f32 v[130:131], v[130:131], v[208:209]
	v_pk_add_f32 v[196:197], v[128:129], v[196:197]
	v_pk_add_f32 v[194:195], v[126:127], v[194:195]
	v_cvt_pk_bf16_f32 v126, v130, v131
	v_cvt_pk_bf16_f32 v127, v132, v133
	v_cvt_pk_bf16_f32 v128, v194, v195
	v_cvt_pk_bf16_f32 v129, v196, v197
	global_store_dwordx4 v2, v[126:129], s[42:43]
	s_nop 1
	v_mul_f32_e32 v126, v131, v131
	v_mul_f32_e32 v127, v133, v133
	v_fmac_f32_e32 v126, v130, v130
	v_fmac_f32_e32 v127, v132, v132
	v_add_f32_e32 v126, v126, v127
	v_mul_f32_e32 v127, v195, v195
	v_fmac_f32_e32 v127, v194, v194
	v_add_f32_e32 v126, v127, v126
	v_mul_f32_e32 v127, v197, v197
	v_fmac_f32_e32 v127, v196, v196
	v_add_f32_e32 v130, v127, v126
	v_lshlrev_b32_e32 v126, 16, v190
	v_and_b32_e32 v127, 0xffff0000, v190
	v_lshlrev_b32_e32 v128, 16, v191
	v_and_b32_e32 v129, 0xffff0000, v191
	v_pk_add_f32 v[124:125], v[124:125], v[128:129]
	v_pk_add_f32 v[122:123], v[122:123], v[126:127]
	v_lshlrev_b32_e32 v126, 16, v192
	v_and_b32_e32 v127, 0xffff0000, v192
	v_lshlrev_b32_e32 v128, 16, v193
	v_and_b32_e32 v129, 0xffff0000, v193
	v_pk_add_f32 v[128:129], v[120:121], v[128:129]
	v_pk_add_f32 v[126:127], v[118:119], v[126:127]
	v_cvt_pk_bf16_f32 v118, v122, v123
	v_cvt_pk_bf16_f32 v119, v124, v125
	v_cvt_pk_bf16_f32 v120, v126, v127
	v_cvt_pk_bf16_f32 v121, v128, v129
	global_store_dwordx4 v2, v[118:121], s[42:43] offset:256
	s_nop 1
	v_mul_f32_e32 v118, v123, v123
	v_mul_f32_e32 v119, v125, v125
	v_fmac_f32_e32 v118, v122, v122
	v_fmac_f32_e32 v119, v124, v124
	v_add_f32_e32 v118, v118, v119
	v_mul_f32_e32 v119, v127, v127
	v_fmac_f32_e32 v119, v126, v126
	v_add_f32_e32 v118, v119, v118
	v_mul_f32_e32 v119, v129, v129
	v_fmac_f32_e32 v119, v128, v128
	v_add_f32_e32 v118, v119, v118
	v_add_f32_e32 v118, v130, v118
	ds_bpermute_b32 v119, v4, v118
	s_waitcnt lgkmcnt(0)
	v_add_f32_e32 v119, v118, v119
	ds_bpermute_b32 v120, v5, v119
	v_lshl_add_u32 v118, v207, 4, s5
	s_and_saveexec_b64 s[42:43], vcc
	s_cbranch_execz .LBB0_1318
	s_waitcnt lgkmcnt(0)
	v_add_f32_e32 v119, v119, v120
	ds_write_b32 v118, v119

; #define PG8_WAIT_V(n) asm volatile("s_waitcnt vmcnt(" #n ")" ::: "memory")
; #define PG8_BAR __builtin_amdgcn_s_barrier()
; template <class Epi, bool ALIGN_EPI = true>
; __device__ __forceinline__ void gemm_phase(LAS unsigned char* lds, const Gemm g, const Sched& S, const Epi& E) {
;     ...
;     PG8_WAIT_V(0);
;     if constexpr (!ALIGN_EPI) { if (wr == 0) PG8_BAR; }
;     PG8_BAR;
;     __device__ __forceinline__ void fused(f32x4 (&acc)[2][2][4][2], const Unit& u, int wr, int wc, int fr, int fq, LAS unsigned char* lds, int wid, int lane) const {
;     ...
;         const unsigned lo2 = (unsigned)(fr * DM + u.pn * BM + wc * 32 + 8 * fq) * 2u;
;         u32x4 hv[2][4][2];
; #pragma unroll
;         for (int ai = 0; ai < 2; ++ai)
; #pragma unroll
;             for (int m = 0; m < 4; ++m) { const char* hb2 = ROWG(HB, u, ai, m, wr, DM, 2);
; #pragma unroll
;                 for (int bj = 0; bj < 2; ++bj) hv[ai][m][bj] = *(const u32x4*)(hb2 + lo2 + bj * HALF * 2); }
.LBB0_2290:
	v_readlane_b32 s54, v246, 44
	v_readlane_b32 s55, v246, 45
	s_add_u32 s14, s54, s6
	v_and_b32_e32 v206, 63, v146
	s_addc_u32 s15, s55, s7
	s_lshl_b32 s6, s4, 9
	v_and_b32_e32 v207, 15, v206
	s_lshl_b32 s7, s5, 6
	v_and_b32_e32 v2, -16, v206
	v_lshlrev_b32_e32 v4, 12, v207
	s_or_b32 s6, s6, s7
	v_add3_u32 v2, s6, v2, v4
	s_lshl_b32 s6, s59, 8
	s_add_i32 s16, s6, s31
	s_ashr_i32 s17, s16, 31
	v_lshl_add_u64 v[4:5], s[14:15], 0, v[2:3]
	s_lshl_b64 s[42:43], s[16:17], 12
	v_lshl_add_u64 v[134:135], v[4:5], 0, s[42:43]
	global_load_dwordx4 v[194:197], v[134:135], off
	global_load_dwordx4 v[190:193], v[134:135], off offset:256
	s_or_b32 s18, s16, 16
	s_ashr_i32 s19, s18, 31
	s_lshl_b64 s[40:41], s[18:19], 12
	s_or_b32 s18, s16, 32
	s_ashr_i32 s19, s18, 31
	s_lshl_b64 s[26:27], s[18:19], 12
	s_or_b32 s18, s16, 48
	s_ashr_i32 s19, s18, 31
	s_lshl_b64 s[24:25], s[18:19], 12
	s_add_i32 s18, s16, 0x80
	s_ashr_i32 s19, s18, 31
	v_lshl_add_u64 v[134:135], v[4:5], 0, s[40:41]
	s_lshl_b64 s[22:23], s[18:19], 12
	s_add_i32 s18, s16, 0x90
	global_load_dwordx4 v[186:189], v[134:135], off
	global_load_dwordx4 v[182:185], v[134:135], off offset:256
	v_lshl_add_u64 v[134:135], v[4:5], 0, s[26:27]
	s_ashr_i32 s19, s18, 31
	global_load_dwordx4 v[178:181], v[134:135], off
	global_load_dwordx4 v[174:177], v[134:135], off offset:256
	v_lshl_add_u64 v[134:135], v[4:5], 0, s[24:25]
	s_lshl_b64 s[20:21], s[18:19], 12
	s_add_i32 s18, s16, 0xa0
	s_addk_i32 s16, 0xb0
	global_load_dwordx4 v[170:173], v[134:135], off
	global_load_dwordx4 v[166:169], v[134:135], off offset:256
	v_lshl_add_u64 v[134:135], v[4:5], 0, s[22:23]
	s_ashr_i32 s19, s18, 31
	s_ashr_i32 s17, s16, 31
	global_load_dwordx4 v[162:165], v[134:135], off
	global_load_dwordx4 v[158:161], v[134:135], off offset:256
	v_lshl_add_u64 v[134:135], v[4:5], 0, s[20:21]
	s_lshl_b64 s[18:19], s[18:19], 12
	s_lshl_b64 s[16:17], s[16:17], 12
	global_load_dwordx4 v[154:157], v[134:135], off
	global_load_dwordx4 v[150:153], v[134:135], off offset:256
	v_lshl_add_u64 v[134:135], v[4:5], 0, s[18:19]
	v_lshl_add_u64 v[4:5], v[4:5], 0, s[16:17]
	global_load_dwordx4 v[142:145], v[134:135], off
	s_nop 0
	global_load_dwordx4 v[134:137], v[134:135], off offset:256
	s_nop 0
	global_load_dwordx4 v[146:149], v[4:5], off
	global_load_dwordx4 v[138:141], v[4:5], off offset:256
	s_waitcnt vmcnt(0)
	s_cmpk_gt_u32 s30, 0xff
	s_cbranch_scc1 .LBB0_2292
	s_barrier
